# GEMM K-loops (6 of 7) rescheduled: LDS frag reads pipelined 2 groups ahead with counted lgkmcnt, GLDS issue spread between MFMA groups, m0 via SALU
# speedup vs baseline: 1.0349x; 1.0349x over previous
; #define WAIT_V0() asm volatile("s_waitcnt vmcnt(0)" ::: "memory")
;     ...
;   GLDS_STAGE(0, 0); WAIT_V0(); __syncthreads();
;   for (int t = 0; t < nt; ++t) {
;     const int cur = t & 1;
;     if (t + 1 < nt) GLDS_STAGE(cur ^ 1, t + 1);
; #pragma unroll
;     for (int ks = 0; ks < KS; ++ks) {
;       bf16x8 At[8], Bf[NB];
; #pragma unroll
;       for (int m = 0; m < 8; ++m) At[m] = *(const bf16x8*)(SA(cur) + lds_byte<KS>(wr * 128 + m * 16 + fr, ks * 32 + fq * 8));
; #pragma unroll
;       for (int n = 0; n < NB; ++n) Bf[n] = *(const bf16x8*)(SB(cur) + lds_byte<KS>(wc * (16 * NB) + n * 16 + fr, ks * 32 + fq * 8));
; #pragma unroll
;       for (int m = 0; m < 8; ++m)
; #pragma unroll
;         for (int n = 0; n < NB; ++n) acc[m][n] = __builtin_amdgcn_mfma_f32_16x16x32_bf16(Bf[n], At[m], acc[m][n], 0, 0, 0);
;       if (xmma) {
;         const bf16x8 Ax = *(const bf16x8*)(SA(cur) + lds_byte<KS>(256 + fr, ks * 32 + fq * 8));
; #pragma unroll
;         for (int n = 0; n < NB; ++n) accx[n] = __builtin_amdgcn_mfma_f32_16x16x32_bf16(Bf[n], Ax, accx[n], 0, 0, 0);
;       }
.LBB0_236:
	s_and_b32 s23, s22, 1
	s_xor_b32 s54, s23, 1
	s_mul_i32 s54, s54, 0x10800
	s_mul_i32 s23, s23, 0x10800
	v_or_b32_e32 v128, s23, v229
	v_add_u32_e32 v223, v128, v191
	v_add_u32_e32 v227, v128, v190
	v_readfirstlane_b32 s100, v180
	ds_read_b128 v[146:149], v223 offset:34816
	ds_read_b128 v[208:211], v227
	ds_read_b128 v[150:153], v223 offset:36864
	ds_read_b128 v[154:157], v223 offset:38912
	ds_read_b128 v[158:161], v223 offset:40960
	ds_read_b128 v[212:215], v227 offset:2048
	s_add_i32 s100, s100, s54
	s_waitcnt lgkmcnt(1)
	v_mfma_f32_16x16x32_bf16 v[142:145], v[146:149], v[208:211], v[142:145]
	v_mfma_f32_16x16x32_bf16 v[138:141], v[150:153], v[208:211], v[138:141]
	v_mfma_f32_16x16x32_bf16 v[134:137], v[154:157], v[208:211], v[134:137]
	v_mfma_f32_16x16x32_bf16 v[130:133], v[158:161], v[208:211], v[130:133]
	ds_read_b128 v[216:219], v227 offset:4096
	s_mov_b32 m0, s100
	v_lshl_add_u64 v[220:221], v[162:163], 0, s[74:75]
	global_load_lds_dwordx4 v[220:221], off
	s_waitcnt lgkmcnt(1)
	v_mfma_f32_16x16x32_bf16 v[124:127], v[146:149], v[212:215], v[124:127]
	v_mfma_f32_16x16x32_bf16 v[120:123], v[150:153], v[212:215], v[120:123]
	v_mfma_f32_16x16x32_bf16 v[116:119], v[154:157], v[212:215], v[116:119]
	v_mfma_f32_16x16x32_bf16 v[92:95], v[158:161], v[212:215], v[92:95]
	ds_read_b128 v[208:211], v227 offset:6144
	s_add_i32 m0, s100, 0x8800
	v_lshl_add_u64 v[220:221], v[170:171], 0, s[74:75]
	global_load_lds_dwordx4 v[220:221], off
	s_waitcnt lgkmcnt(1)
	v_mfma_f32_16x16x32_bf16 v[60:63], v[146:149], v[216:219], v[60:63]
	v_mfma_f32_16x16x32_bf16 v[40:43], v[150:153], v[216:219], v[40:43]
	v_mfma_f32_16x16x32_bf16 v[36:39], v[154:157], v[216:219], v[36:39]
	v_mfma_f32_16x16x32_bf16 v[32:35], v[158:161], v[216:219], v[32:35]
	ds_read_b128 v[212:215], v227 offset:8192
	s_add_i32 m0, s100, 0x2000
	v_lshl_add_u64 v[220:221], v[164:165], 0, s[74:75]
	global_load_lds_dwordx4 v[220:221], off
	s_waitcnt lgkmcnt(1)
	v_mfma_f32_16x16x32_bf16 v[28:31], v[146:149], v[208:211], v[28:31]
	v_mfma_f32_16x16x32_bf16 v[24:27], v[150:153], v[208:211], v[24:27]
	v_mfma_f32_16x16x32_bf16 v[20:23], v[154:157], v[208:211], v[20:23]
	v_mfma_f32_16x16x32_bf16 v[16:19], v[158:161], v[208:211], v[16:19]
	ds_read_b128 v[216:219], v227 offset:10240
	s_add_i32 m0, s100, 0xa800
	v_lshl_add_u64 v[220:221], v[172:173], 0, s[74:75]
	global_load_lds_dwordx4 v[220:221], off
	s_waitcnt lgkmcnt(1)
	v_mfma_f32_16x16x32_bf16 v[84:87], v[146:149], v[212:215], v[84:87]
	v_mfma_f32_16x16x32_bf16 v[100:103], v[150:153], v[212:215], v[100:103]
	v_mfma_f32_16x16x32_bf16 v[108:111], v[154:157], v[212:215], v[108:111]
	v_mfma_f32_16x16x32_bf16 v[48:51], v[158:161], v[212:215], v[48:51]
	ds_read_b128 v[192:195], v223 offset:35840
	ds_read_b128 v[208:211], v227 offset:12288
	s_add_i32 m0, s100, 0x4000
	v_lshl_add_u64 v[220:221], v[166:167], 0, s[74:75]
	global_load_lds_dwordx4 v[220:221], off
	s_waitcnt lgkmcnt(2)
	v_mfma_f32_16x16x32_bf16 v[44:47], v[146:149], v[216:219], v[44:47]
	v_mfma_f32_16x16x32_bf16 v[64:67], v[150:153], v[216:219], v[64:67]
	v_mfma_f32_16x16x32_bf16 v[72:75], v[154:157], v[216:219], v[72:75]
	v_mfma_f32_16x16x32_bf16 v[76:79], v[158:161], v[216:219], v[76:79]
	ds_read_b128 v[196:199], v223 offset:37888
	ds_read_b128 v[212:215], v227 offset:14336
	s_add_i32 m0, s100, 0xc800
	v_lshl_add_u64 v[220:221], v[174:175], 0, s[74:75]
	global_load_lds_dwordx4 v[220:221], off
	s_waitcnt lgkmcnt(2)
	v_mfma_f32_16x16x32_bf16 v[96:99], v[146:149], v[208:211], v[96:99]
	v_mfma_f32_16x16x32_bf16 v[104:107], v[150:153], v[208:211], v[104:107]
	v_mfma_f32_16x16x32_bf16 v[112:115], v[154:157], v[208:211], v[112:115]
	v_mfma_f32_16x16x32_bf16 v[56:59], v[158:161], v[208:211], v[56:59]
	ds_read_b128 v[200:203], v223 offset:39936
	ds_read_b128 v[216:219], v227 offset:1024
	s_add_i32 m0, s100, 0x6000
	v_lshl_add_u64 v[220:221], v[168:169], 0, s[74:75]
	global_load_lds_dwordx4 v[220:221], off
	s_waitcnt lgkmcnt(2)
	v_mfma_f32_16x16x32_bf16 v[52:55], v[146:149], v[212:215], v[52:55]
	v_mfma_f32_16x16x32_bf16 v[68:71], v[150:153], v[212:215], v[68:71]
	v_mfma_f32_16x16x32_bf16 v[80:83], v[154:157], v[212:215], v[80:83]
	v_mfma_f32_16x16x32_bf16 v[88:91], v[158:161], v[212:215], v[88:91]
	ds_read_b128 v[204:207], v223 offset:41984
	ds_read_b128 v[208:211], v227 offset:3072
	s_add_i32 m0, s100, 0xe800
	v_lshl_add_u64 v[220:221], v[176:177], 0, s[74:75]
	global_load_lds_dwordx4 v[220:221], off
	s_waitcnt lgkmcnt(1)
	v_mfma_f32_16x16x32_bf16 v[142:145], v[192:195], v[216:219], v[142:145]
	v_mfma_f32_16x16x32_bf16 v[138:141], v[196:199], v[216:219], v[138:141]
	v_mfma_f32_16x16x32_bf16 v[134:137], v[200:203], v[216:219], v[134:137]
	v_mfma_f32_16x16x32_bf16 v[130:133], v[204:207], v[216:219], v[130:133]
	ds_read_b128 v[212:215], v227 offset:5120
	s_and_saveexec_b64 s[20:21], s[8:9]
	s_cbranch_execz .Lgk_inproj_xl
	v_readfirstlane_b32 s101, v189
	s_add_i32 s101, s101, s54
	s_add_i32 m0, s101, 0x8000
	v_lshl_add_u64 v[220:221], v[178:179], 0, s[74:75]
	global_load_lds_dwordx4 v[220:221], off
;     ...
;     for (int ks = 0; ks < KS; ++ks) {
;       bf16x8 At[8], Bf[NB];
; #pragma unroll
;       for (int m = 0; m < 8; ++m) At[m] = *(const bf16x8*)(SA(cur) + lds_byte<KS>(wr * 128 + m * 16 + fr, ks * 32 + fq * 8));
; #pragma unroll
;       for (int n = 0; n < NB; ++n) Bf[n] = *(const bf16x8*)(SB(cur) + lds_byte<KS>(wc * (16 * NB) + n * 16 + fr, ks * 32 + fq * 8));
; #pragma unroll
;       for (int m = 0; m < 8; ++m)
; #pragma unroll
;         for (int n = 0; n < NB; ++n) acc[m][n] = __builtin_amdgcn_mfma_f32_16x16x32_bf16(Bf[n], At[m], acc[m][n], 0, 0, 0);
;       if (xmma) {
;         const bf16x8 Ax = *(const bf16x8*)(SA(cur) + lds_byte<KS>(256 + fr, ks * 32 + fq * 8));
; #pragma unroll
;         for (int n = 0; n < NB; ++n) accx[n] = __builtin_amdgcn_mfma_f32_16x16x32_bf16(Bf[n], Ax, accx[n], 0, 0, 0);
;       }
.Lgk_inproj_xl:
	s_or_b64 exec, exec, s[20:21]
	s_waitcnt lgkmcnt(1)
	v_mfma_f32_16x16x32_bf16 v[124:127], v[192:195], v[208:211], v[124:127]
	v_mfma_f32_16x16x32_bf16 v[120:123], v[196:199], v[208:211], v[120:123]
	v_mfma_f32_16x16x32_bf16 v[116:119], v[200:203], v[208:211], v[116:119]
	v_mfma_f32_16x16x32_bf16 v[92:95], v[204:207], v[208:211], v[92:95]
	ds_read_b128 v[216:219], v227 offset:7168
	s_waitcnt lgkmcnt(1)
	v_mfma_f32_16x16x32_bf16 v[60:63], v[192:195], v[212:215], v[60:63]
	v_mfma_f32_16x16x32_bf16 v[40:43], v[196:199], v[212:215], v[40:43]
	v_mfma_f32_16x16x32_bf16 v[36:39], v[200:203], v[212:215], v[36:39]
	v_mfma_f32_16x16x32_bf16 v[32:35], v[204:207], v[212:215], v[32:35]
	ds_read_b128 v[208:211], v227 offset:9216
	s_waitcnt lgkmcnt(1)
	v_mfma_f32_16x16x32_bf16 v[28:31], v[192:195], v[216:219], v[28:31]
	v_mfma_f32_16x16x32_bf16 v[24:27], v[196:199], v[216:219], v[24:27]
	v_mfma_f32_16x16x32_bf16 v[20:23], v[200:203], v[216:219], v[20:23]
	v_mfma_f32_16x16x32_bf16 v[16:19], v[204:207], v[216:219], v[16:19]
	ds_read_b128 v[212:215], v227 offset:11264
	s_waitcnt lgkmcnt(1)
	v_mfma_f32_16x16x32_bf16 v[84:87], v[192:195], v[208:211], v[84:87]
	v_mfma_f32_16x16x32_bf16 v[100:103], v[196:199], v[208:211], v[100:103]
	v_mfma_f32_16x16x32_bf16 v[108:111], v[200:203], v[208:211], v[108:111]
	v_mfma_f32_16x16x32_bf16 v[48:51], v[204:207], v[208:211], v[48:51]
	ds_read_b128 v[216:219], v227 offset:13312
	s_waitcnt lgkmcnt(1)
	v_mfma_f32_16x16x32_bf16 v[44:47], v[192:195], v[212:215], v[44:47]
	v_mfma_f32_16x16x32_bf16 v[64:67], v[196:199], v[212:215], v[64:67]
	v_mfma_f32_16x16x32_bf16 v[72:75], v[200:203], v[212:215], v[72:75]
	v_mfma_f32_16x16x32_bf16 v[76:79], v[204:207], v[212:215], v[76:79]
	ds_read_b128 v[208:211], v227 offset:15360
	s_waitcnt lgkmcnt(1)
	v_mfma_f32_16x16x32_bf16 v[96:99], v[192:195], v[216:219], v[96:99]
	v_mfma_f32_16x16x32_bf16 v[104:107], v[196:199], v[216:219], v[104:107]
	v_mfma_f32_16x16x32_bf16 v[112:115], v[200:203], v[216:219], v[112:115]
	v_mfma_f32_16x16x32_bf16 v[56:59], v[204:207], v[216:219], v[56:59]
	s_waitcnt lgkmcnt(0)
	v_mfma_f32_16x16x32_bf16 v[52:55], v[192:195], v[208:211], v[52:55]
	v_mfma_f32_16x16x32_bf16 v[68:71], v[196:199], v[208:211], v[68:71]
	v_mfma_f32_16x16x32_bf16 v[80:83], v[200:203], v[208:211], v[80:83]
	v_mfma_f32_16x16x32_bf16 v[88:91], v[204:207], v[208:211], v[88:91]
	s_and_saveexec_b64 s[20:21], s[6:7]
	s_cbranch_execz .LBB0_235
	v_add_u32_e32 v230, s23, v229
	ds_read_b128 v[212:215], v230 offset:32768
	ds_read_b128 v[216:219], v230 offset:33792
	s_waitcnt lgkmcnt(1)
	v_mfma_f32_16x16x32_bf16 v[12:15], v[146:149], v[212:215], v[12:15]
	v_mfma_f32_16x16x32_bf16 v[4:7], v[150:153], v[212:215], v[4:7]
	v_mfma_f32_16x16x32_bf16 v[8:11], v[154:157], v[212:215], v[8:11]
	v_mfma_f32_16x16x32_bf16 v[0:3], v[158:161], v[212:215], v[0:3]
	s_waitcnt lgkmcnt(0)
	v_mfma_f32_16x16x32_bf16 v[12:15], v[192:195], v[216:219], v[12:15]
	v_mfma_f32_16x16x32_bf16 v[4:7], v[196:199], v[216:219], v[4:7]
	v_mfma_f32_16x16x32_bf16 v[8:11], v[200:203], v[216:219], v[8:11]
	v_mfma_f32_16x16x32_bf16 v[0:3], v[204:207], v[216:219], v[0:3]
	s_branch .LBB0_235

; #define WAIT_V0() asm volatile("s_waitcnt vmcnt(0)" ::: "memory")
;     ...
;   GLDS_STAGE(0, 0); WAIT_V0(); __syncthreads();
;   for (int t = 0; t < nt; ++t) {
;     const int cur = t & 1;
;     if (t + 1 < nt) GLDS_STAGE(cur ^ 1, t + 1);
; #pragma unroll
;     for (int ks = 0; ks < KS; ++ks) {
;       bf16x8 At[8], Bf[NB];
; #pragma unroll
;       for (int m = 0; m < 8; ++m) At[m] = *(const bf16x8*)(SA(cur) + lds_byte<KS>(wr * 128 + m * 16 + fr, ks * 32 + fq * 8));
; #pragma unroll
;       for (int n = 0; n < NB; ++n) Bf[n] = *(const bf16x8*)(SB(cur) + lds_byte<KS>(wc * (16 * NB) + n * 16 + fr, ks * 32 + fq * 8));
; #pragma unroll
;       for (int m = 0; m < 8; ++m)
; #pragma unroll
;         for (int n = 0; n < NB; ++n) acc[m][n] = __builtin_amdgcn_mfma_f32_16x16x32_bf16(Bf[n], At[m], acc[m][n], 0, 0, 0);
;       if (xmma) {
;         const bf16x8 Ax = *(const bf16x8*)(SA(cur) + lds_byte<KS>(256 + fr, ks * 32 + fq * 8));
; #pragma unroll
;         for (int n = 0; n < NB; ++n) accx[n] = __builtin_amdgcn_mfma_f32_16x16x32_bf16(Bf[n], Ax, accx[n], 0, 0, 0);
;       }
.LBB0_279:
	s_and_b32 s75, s23, 1
	s_xor_b32 s76, s75, 1
	s_mul_i32 s76, s76, 0x10800
	s_mul_i32 s75, s75, 0x10800
	v_or_b32_e32 v128, s75, v184
	v_add_u32_e32 v226, v128, v195
	v_add_u32_e32 v227, v128, v194
	v_readfirstlane_b32 s100, v183
	ds_read_b128 v[146:149], v226 offset:34816
	ds_read_b128 v[212:215], v227
	ds_read_b128 v[150:153], v226 offset:36864
	ds_read_b128 v[154:157], v226 offset:38912
	ds_read_b128 v[158:161], v226 offset:40960
	ds_read_b128 v[216:219], v227 offset:2048
	s_add_i32 s100, s100, s76
	s_waitcnt lgkmcnt(1)
	v_mfma_f32_16x16x32_bf16 v[142:145], v[146:149], v[212:215], v[142:145]
	v_mfma_f32_16x16x32_bf16 v[138:141], v[150:153], v[212:215], v[138:141]
	v_mfma_f32_16x16x32_bf16 v[134:137], v[154:157], v[212:215], v[134:137]
	v_mfma_f32_16x16x32_bf16 v[130:133], v[158:161], v[212:215], v[130:133]
	ds_read_b128 v[220:223], v227 offset:4096
	s_mov_b32 m0, s100
	v_lshl_add_u64 v[224:225], v[162:163], 0, s[66:67]
	global_load_lds_dwordx4 v[224:225], off
	s_waitcnt lgkmcnt(1)
	v_mfma_f32_16x16x32_bf16 v[124:127], v[146:149], v[216:219], v[124:127]
	v_mfma_f32_16x16x32_bf16 v[120:123], v[150:153], v[216:219], v[120:123]
	v_mfma_f32_16x16x32_bf16 v[116:119], v[154:157], v[216:219], v[116:119]
	v_mfma_f32_16x16x32_bf16 v[112:115], v[158:161], v[216:219], v[112:115]
	ds_read_b128 v[212:215], v227 offset:6144
	s_add_i32 m0, s100, 0x8800
	v_lshl_add_u64 v[224:225], v[172:173], 0, s[66:67]
	global_load_lds_dwordx4 v[224:225], off
	s_waitcnt lgkmcnt(1)
	v_mfma_f32_16x16x32_bf16 v[108:111], v[146:149], v[220:223], v[108:111]
	v_mfma_f32_16x16x32_bf16 v[104:107], v[150:153], v[220:223], v[104:107]
	v_mfma_f32_16x16x32_bf16 v[100:103], v[154:157], v[220:223], v[100:103]
	v_mfma_f32_16x16x32_bf16 v[96:99], v[158:161], v[220:223], v[96:99]
	ds_read_b128 v[216:219], v227 offset:8192
	s_add_i32 m0, s100, 0x2000
	v_lshl_add_u64 v[224:225], v[164:165], 0, s[66:67]
	global_load_lds_dwordx4 v[224:225], off
	s_waitcnt lgkmcnt(1)
	v_mfma_f32_16x16x32_bf16 v[92:95], v[146:149], v[212:215], v[92:95]
	v_mfma_f32_16x16x32_bf16 v[88:91], v[150:153], v[212:215], v[88:91]
	v_mfma_f32_16x16x32_bf16 v[84:87], v[154:157], v[212:215], v[84:87]
	v_mfma_f32_16x16x32_bf16 v[80:83], v[158:161], v[212:215], v[80:83]
	ds_read_b128 v[220:223], v227 offset:10240
	s_add_i32 m0, s100, 0xa800
	v_lshl_add_u64 v[224:225], v[174:175], 0, s[66:67]
	global_load_lds_dwordx4 v[224:225], off
	s_waitcnt lgkmcnt(1)
	v_mfma_f32_16x16x32_bf16 v[76:79], v[146:149], v[216:219], v[76:79]
	v_mfma_f32_16x16x32_bf16 v[72:75], v[150:153], v[216:219], v[72:75]
	v_mfma_f32_16x16x32_bf16 v[68:71], v[154:157], v[216:219], v[68:71]
	v_mfma_f32_16x16x32_bf16 v[64:67], v[158:161], v[216:219], v[64:67]
	ds_read_b128 v[196:199], v226 offset:35840
	ds_read_b128 v[212:215], v227 offset:12288
	s_add_i32 m0, s100, 0x4000
	v_lshl_add_u64 v[224:225], v[168:169], 0, s[66:67]
	global_load_lds_dwordx4 v[224:225], off
	s_waitcnt lgkmcnt(2)
	v_mfma_f32_16x16x32_bf16 v[60:63], v[146:149], v[220:223], v[60:63]
	v_mfma_f32_16x16x32_bf16 v[56:59], v[150:153], v[220:223], v[56:59]
	v_mfma_f32_16x16x32_bf16 v[52:55], v[154:157], v[220:223], v[52:55]
	v_mfma_f32_16x16x32_bf16 v[48:51], v[158:161], v[220:223], v[48:51]
	ds_read_b128 v[200:203], v226 offset:37888
	ds_read_b128 v[216:219], v227 offset:14336
	s_add_i32 m0, s100, 0xc800
	v_lshl_add_u64 v[224:225], v[176:177], 0, s[66:67]
	global_load_lds_dwordx4 v[224:225], off
	s_waitcnt lgkmcnt(2)
	v_mfma_f32_16x16x32_bf16 v[44:47], v[146:149], v[212:215], v[44:47]
	v_mfma_f32_16x16x32_bf16 v[40:43], v[150:153], v[212:215], v[40:43]
	v_mfma_f32_16x16x32_bf16 v[36:39], v[154:157], v[212:215], v[36:39]
	v_mfma_f32_16x16x32_bf16 v[32:35], v[158:161], v[212:215], v[32:35]
	ds_read_b128 v[204:207], v226 offset:39936
	ds_read_b128 v[220:223], v227 offset:1024
	s_add_i32 m0, s100, 0x6000
	v_lshl_add_u64 v[224:225], v[170:171], 0, s[66:67]
	global_load_lds_dwordx4 v[224:225], off
	s_waitcnt lgkmcnt(2)
	v_mfma_f32_16x16x32_bf16 v[28:31], v[146:149], v[216:219], v[28:31]
	v_mfma_f32_16x16x32_bf16 v[24:27], v[150:153], v[216:219], v[24:27]
	v_mfma_f32_16x16x32_bf16 v[20:23], v[154:157], v[216:219], v[20:23]
	v_mfma_f32_16x16x32_bf16 v[16:19], v[158:161], v[216:219], v[16:19]
	ds_read_b128 v[208:211], v226 offset:41984
	ds_read_b128 v[212:215], v227 offset:3072
	s_add_i32 m0, s100, 0xe800
	v_lshl_add_u64 v[224:225], v[178:179], 0, s[66:67]
	global_load_lds_dwordx4 v[224:225], off
	s_waitcnt lgkmcnt(1)
	v_mfma_f32_16x16x32_bf16 v[142:145], v[196:199], v[220:223], v[142:145]
	v_mfma_f32_16x16x32_bf16 v[138:141], v[200:203], v[220:223], v[138:141]
	v_mfma_f32_16x16x32_bf16 v[134:137], v[204:207], v[220:223], v[134:137]
	v_mfma_f32_16x16x32_bf16 v[130:133], v[208:211], v[220:223], v[130:133]
	ds_read_b128 v[216:219], v227 offset:5120
	s_and_saveexec_b64 s[20:21], s[64:65]
	s_cbranch_execz .Lgk_upproj_xl
	v_readfirstlane_b32 s101, v193
	s_add_i32 s101, s101, s76
	s_add_i32 m0, s101, 0x8000
	v_lshl_add_u64 v[224:225], v[180:181], 0, s[66:67]
	global_load_lds_dwordx4 v[224:225], off
;     ...
;     for (int ks = 0; ks < KS; ++ks) {
;       bf16x8 At[8], Bf[NB];
; #pragma unroll
;       for (int m = 0; m < 8; ++m) At[m] = *(const bf16x8*)(SA(cur) + lds_byte<KS>(wr * 128 + m * 16 + fr, ks * 32 + fq * 8));
; #pragma unroll
;       for (int n = 0; n < NB; ++n) Bf[n] = *(const bf16x8*)(SB(cur) + lds_byte<KS>(wc * (16 * NB) + n * 16 + fr, ks * 32 + fq * 8));
; #pragma unroll
;       for (int m = 0; m < 8; ++m)
; #pragma unroll
;         for (int n = 0; n < NB; ++n) acc[m][n] = __builtin_amdgcn_mfma_f32_16x16x32_bf16(Bf[n], At[m], acc[m][n], 0, 0, 0);
;       if (xmma) {
;         const bf16x8 Ax = *(const bf16x8*)(SA(cur) + lds_byte<KS>(256 + fr, ks * 32 + fq * 8));
; #pragma unroll
;         for (int n = 0; n < NB; ++n) accx[n] = __builtin_amdgcn_mfma_f32_16x16x32_bf16(Bf[n], Ax, accx[n], 0, 0, 0);
;       }
.Lgk_upproj_xl:
	s_or_b64 exec, exec, s[20:21]
	s_waitcnt lgkmcnt(1)
	v_mfma_f32_16x16x32_bf16 v[124:127], v[196:199], v[212:215], v[124:127]
	v_mfma_f32_16x16x32_bf16 v[120:123], v[200:203], v[212:215], v[120:123]
	v_mfma_f32_16x16x32_bf16 v[116:119], v[204:207], v[212:215], v[116:119]
	v_mfma_f32_16x16x32_bf16 v[112:115], v[208:211], v[212:215], v[112:115]
	ds_read_b128 v[220:223], v227 offset:7168
	s_waitcnt lgkmcnt(1)
	v_mfma_f32_16x16x32_bf16 v[108:111], v[196:199], v[216:219], v[108:111]
	v_mfma_f32_16x16x32_bf16 v[104:107], v[200:203], v[216:219], v[104:107]
	v_mfma_f32_16x16x32_bf16 v[100:103], v[204:207], v[216:219], v[100:103]
	v_mfma_f32_16x16x32_bf16 v[96:99], v[208:211], v[216:219], v[96:99]
	ds_read_b128 v[212:215], v227 offset:9216
	s_waitcnt lgkmcnt(1)
	v_mfma_f32_16x16x32_bf16 v[92:95], v[196:199], v[220:223], v[92:95]
	v_mfma_f32_16x16x32_bf16 v[88:91], v[200:203], v[220:223], v[88:91]
	v_mfma_f32_16x16x32_bf16 v[84:87], v[204:207], v[220:223], v[84:87]
	v_mfma_f32_16x16x32_bf16 v[80:83], v[208:211], v[220:223], v[80:83]
	ds_read_b128 v[216:219], v227 offset:11264
	s_waitcnt lgkmcnt(1)
	v_mfma_f32_16x16x32_bf16 v[76:79], v[196:199], v[212:215], v[76:79]
	v_mfma_f32_16x16x32_bf16 v[72:75], v[200:203], v[212:215], v[72:75]
	v_mfma_f32_16x16x32_bf16 v[68:71], v[204:207], v[212:215], v[68:71]
	v_mfma_f32_16x16x32_bf16 v[64:67], v[208:211], v[212:215], v[64:67]
	ds_read_b128 v[220:223], v227 offset:13312
	s_waitcnt lgkmcnt(1)
	v_mfma_f32_16x16x32_bf16 v[60:63], v[196:199], v[216:219], v[60:63]
	v_mfma_f32_16x16x32_bf16 v[56:59], v[200:203], v[216:219], v[56:59]
	v_mfma_f32_16x16x32_bf16 v[52:55], v[204:207], v[216:219], v[52:55]
	v_mfma_f32_16x16x32_bf16 v[48:51], v[208:211], v[216:219], v[48:51]
	ds_read_b128 v[212:215], v227 offset:15360
	s_waitcnt lgkmcnt(1)
	v_mfma_f32_16x16x32_bf16 v[44:47], v[196:199], v[220:223], v[44:47]
	v_mfma_f32_16x16x32_bf16 v[40:43], v[200:203], v[220:223], v[40:43]
	v_mfma_f32_16x16x32_bf16 v[36:39], v[204:207], v[220:223], v[36:39]
	v_mfma_f32_16x16x32_bf16 v[32:35], v[208:211], v[220:223], v[32:35]
	s_waitcnt lgkmcnt(0)
	v_mfma_f32_16x16x32_bf16 v[28:31], v[196:199], v[212:215], v[28:31]
	v_mfma_f32_16x16x32_bf16 v[24:27], v[200:203], v[212:215], v[24:27]
	v_mfma_f32_16x16x32_bf16 v[20:23], v[204:207], v[212:215], v[20:23]
	v_mfma_f32_16x16x32_bf16 v[16:19], v[208:211], v[212:215], v[16:19]
	s_and_saveexec_b64 s[20:21], s[18:19]
	s_cbranch_execz .LBB0_278
	v_add_u32_e32 v228, s75, v184
	ds_read_b128 v[216:219], v228 offset:32768
	ds_read_b128 v[220:223], v228 offset:33792
	s_waitcnt lgkmcnt(1)
	v_mfma_f32_16x16x32_bf16 v[12:15], v[146:149], v[216:219], v[12:15]
	v_mfma_f32_16x16x32_bf16 v[8:11], v[150:153], v[216:219], v[8:11]
	v_mfma_f32_16x16x32_bf16 v[4:7], v[154:157], v[216:219], v[4:7]
	v_mfma_f32_16x16x32_bf16 v[0:3], v[158:161], v[216:219], v[0:3]
	s_waitcnt lgkmcnt(0)
	v_mfma_f32_16x16x32_bf16 v[12:15], v[196:199], v[220:223], v[12:15]
	v_mfma_f32_16x16x32_bf16 v[8:11], v[200:203], v[220:223], v[8:11]
	v_mfma_f32_16x16x32_bf16 v[4:7], v[204:207], v[220:223], v[4:7]
	v_mfma_f32_16x16x32_bf16 v[0:3], v[208:211], v[220:223], v[0:3]
	s_branch .LBB0_278

; #define WAIT_V0() asm volatile("s_waitcnt vmcnt(0)" ::: "memory")
;     ...
;   GLDS_STAGE(0, 0); WAIT_V0(); __syncthreads();
;   for (int t = 0; t < nt; ++t) {
;     const int cur = t & 1;
;     if (t + 1 < nt) GLDS_STAGE(cur ^ 1, t + 1);
; #pragma unroll
;     for (int ks = 0; ks < KS; ++ks) {
;       bf16x8 At[8], Bf[NB];
; #pragma unroll
;       for (int m = 0; m < 8; ++m) At[m] = *(const bf16x8*)(SA(cur) + lds_byte<KS>(wr * 128 + m * 16 + fr, ks * 32 + fq * 8));
; #pragma unroll
;       for (int n = 0; n < NB; ++n) Bf[n] = *(const bf16x8*)(SB(cur) + lds_byte<KS>(wc * (16 * NB) + n * 16 + fr, ks * 32 + fq * 8));
; #pragma unroll
;       for (int m = 0; m < 8; ++m)
; #pragma unroll
;         for (int n = 0; n < NB; ++n) acc[m][n] = __builtin_amdgcn_mfma_f32_16x16x32_bf16(Bf[n], At[m], acc[m][n], 0, 0, 0);
;       if (xmma) {
;         const bf16x8 Ax = *(const bf16x8*)(SA(cur) + lds_byte<KS>(256 + fr, ks * 32 + fq * 8));
; #pragma unroll
;         for (int n = 0; n < NB; ++n) accx[n] = __builtin_amdgcn_mfma_f32_16x16x32_bf16(Bf[n], Ax, accx[n], 0, 0, 0);
;       }
.LBB0_1295:
	s_and_b32 s22, s15, 1
	s_xor_b32 s23, s22, 1
	s_mul_i32 s23, s23, 0x10800
	s_mul_i32 s22, s22, 0x10800
	v_or_b32_e32 v195, s22, v182
	v_add_u32_e32 v226, v195, v194
	v_add_u32_e32 v227, v195, v193
	v_readfirstlane_b32 s100, v183
	ds_read_b128 v[146:149], v226 offset:34816
	ds_read_b128 v[212:215], v227
	ds_read_b128 v[150:153], v226 offset:36864
	ds_read_b128 v[154:157], v226 offset:38912
	ds_read_b128 v[158:161], v226 offset:40960
	ds_read_b128 v[216:219], v227 offset:2048
	s_add_i32 s100, s100, s23
	s_waitcnt lgkmcnt(1)
	v_mfma_f32_16x16x32_bf16 v[142:145], v[146:149], v[212:215], v[142:145]
	v_mfma_f32_16x16x32_bf16 v[138:141], v[150:153], v[212:215], v[138:141]
	v_mfma_f32_16x16x32_bf16 v[134:137], v[154:157], v[212:215], v[134:137]
	v_mfma_f32_16x16x32_bf16 v[130:133], v[158:161], v[212:215], v[130:133]
	ds_read_b128 v[220:223], v227 offset:4096
	s_mov_b32 m0, s100
	v_lshl_add_u64 v[224:225], v[162:163], 0, s[64:65]
	global_load_lds_dwordx4 v[224:225], off
	s_waitcnt lgkmcnt(1)
	v_mfma_f32_16x16x32_bf16 v[124:127], v[146:149], v[216:219], v[124:127]
	v_mfma_f32_16x16x32_bf16 v[120:123], v[150:153], v[216:219], v[120:123]
	v_mfma_f32_16x16x32_bf16 v[116:119], v[154:157], v[216:219], v[116:119]
	v_mfma_f32_16x16x32_bf16 v[112:115], v[158:161], v[216:219], v[112:115]
	ds_read_b128 v[212:215], v227 offset:6144
	s_add_i32 m0, s100, 0x8800
	v_lshl_add_u64 v[224:225], v[170:171], 0, s[64:65]
	global_load_lds_dwordx4 v[224:225], off
	s_waitcnt lgkmcnt(1)
	v_mfma_f32_16x16x32_bf16 v[108:111], v[146:149], v[220:223], v[108:111]
	v_mfma_f32_16x16x32_bf16 v[104:107], v[150:153], v[220:223], v[104:107]
	v_mfma_f32_16x16x32_bf16 v[100:103], v[154:157], v[220:223], v[100:103]
	v_mfma_f32_16x16x32_bf16 v[96:99], v[158:161], v[220:223], v[96:99]
	ds_read_b128 v[216:219], v227 offset:8192
	s_add_i32 m0, s100, 0x2000
	v_lshl_add_u64 v[224:225], v[164:165], 0, s[64:65]
	global_load_lds_dwordx4 v[224:225], off
	s_waitcnt lgkmcnt(1)
	v_mfma_f32_16x16x32_bf16 v[92:95], v[146:149], v[212:215], v[92:95]
	v_mfma_f32_16x16x32_bf16 v[88:91], v[150:153], v[212:215], v[88:91]
	v_mfma_f32_16x16x32_bf16 v[84:87], v[154:157], v[212:215], v[84:87]
	v_mfma_f32_16x16x32_bf16 v[80:83], v[158:161], v[212:215], v[80:83]
	ds_read_b128 v[220:223], v227 offset:10240
	s_add_i32 m0, s100, 0xa800
	v_lshl_add_u64 v[224:225], v[172:173], 0, s[64:65]
	global_load_lds_dwordx4 v[224:225], off
	s_waitcnt lgkmcnt(1)
	v_mfma_f32_16x16x32_bf16 v[76:79], v[146:149], v[216:219], v[76:79]
	v_mfma_f32_16x16x32_bf16 v[72:75], v[150:153], v[216:219], v[72:75]
	v_mfma_f32_16x16x32_bf16 v[68:71], v[154:157], v[216:219], v[68:71]
	v_mfma_f32_16x16x32_bf16 v[64:67], v[158:161], v[216:219], v[64:67]
	ds_read_b128 v[196:199], v226 offset:35840
	ds_read_b128 v[212:215], v227 offset:12288
	s_add_i32 m0, s100, 0x4000
	v_lshl_add_u64 v[224:225], v[166:167], 0, s[64:65]
	global_load_lds_dwordx4 v[224:225], off
	s_waitcnt lgkmcnt(2)
	v_mfma_f32_16x16x32_bf16 v[60:63], v[146:149], v[220:223], v[60:63]
	v_mfma_f32_16x16x32_bf16 v[56:59], v[150:153], v[220:223], v[56:59]
	v_mfma_f32_16x16x32_bf16 v[52:55], v[154:157], v[220:223], v[52:55]
	v_mfma_f32_16x16x32_bf16 v[48:51], v[158:161], v[220:223], v[48:51]
	ds_read_b128 v[200:203], v226 offset:37888
	ds_read_b128 v[216:219], v227 offset:14336
	s_add_i32 m0, s100, 0xc800
	v_lshl_add_u64 v[224:225], v[174:175], 0, s[64:65]
	global_load_lds_dwordx4 v[224:225], off
	s_waitcnt lgkmcnt(2)
	v_mfma_f32_16x16x32_bf16 v[44:47], v[146:149], v[212:215], v[44:47]
	v_mfma_f32_16x16x32_bf16 v[40:43], v[150:153], v[212:215], v[40:43]
	v_mfma_f32_16x16x32_bf16 v[36:39], v[154:157], v[212:215], v[36:39]
	v_mfma_f32_16x16x32_bf16 v[32:35], v[158:161], v[212:215], v[32:35]
	ds_read_b128 v[204:207], v226 offset:39936
	ds_read_b128 v[220:223], v227 offset:1024
	s_add_i32 m0, s100, 0x6000
	v_lshl_add_u64 v[224:225], v[168:169], 0, s[64:65]
	global_load_lds_dwordx4 v[224:225], off
	s_waitcnt lgkmcnt(2)
	v_mfma_f32_16x16x32_bf16 v[28:31], v[146:149], v[216:219], v[28:31]
	v_mfma_f32_16x16x32_bf16 v[24:27], v[150:153], v[216:219], v[24:27]
	v_mfma_f32_16x16x32_bf16 v[20:23], v[154:157], v[216:219], v[20:23]
	v_mfma_f32_16x16x32_bf16 v[16:19], v[158:161], v[216:219], v[16:19]
	ds_read_b128 v[208:211], v226 offset:41984
	ds_read_b128 v[212:215], v227 offset:3072
	s_add_i32 m0, s100, 0xe800
	v_lshl_add_u64 v[224:225], v[176:177], 0, s[64:65]
	global_load_lds_dwordx4 v[224:225], off
	s_waitcnt lgkmcnt(1)
	v_mfma_f32_16x16x32_bf16 v[142:145], v[196:199], v[220:223], v[142:145]
	v_mfma_f32_16x16x32_bf16 v[138:141], v[200:203], v[220:223], v[138:141]
	v_mfma_f32_16x16x32_bf16 v[134:137], v[204:207], v[220:223], v[134:137]
	v_mfma_f32_16x16x32_bf16 v[130:133], v[208:211], v[220:223], v[130:133]
	ds_read_b128 v[216:219], v227 offset:5120
	s_and_saveexec_b64 s[20:21], s[18:19]
	s_cbranch_execz .Lgk_gates_xl
	v_readfirstlane_b32 s101, v192
	s_add_i32 s101, s101, s23
	s_add_i32 m0, s101, 0x8000
	v_lshl_add_u64 v[224:225], v[178:179], 0, s[64:65]
	global_load_lds_dwordx4 v[224:225], off
;     ...
;     for (int ks = 0; ks < KS; ++ks) {
;       bf16x8 At[8], Bf[NB];
; #pragma unroll
;       for (int m = 0; m < 8; ++m) At[m] = *(const bf16x8*)(SA(cur) + lds_byte<KS>(wr * 128 + m * 16 + fr, ks * 32 + fq * 8));
; #pragma unroll
;       for (int n = 0; n < NB; ++n) Bf[n] = *(const bf16x8*)(SB(cur) + lds_byte<KS>(wc * (16 * NB) + n * 16 + fr, ks * 32 + fq * 8));
; #pragma unroll
;       for (int m = 0; m < 8; ++m)
; #pragma unroll
;         for (int n = 0; n < NB; ++n) acc[m][n] = __builtin_amdgcn_mfma_f32_16x16x32_bf16(Bf[n], At[m], acc[m][n], 0, 0, 0);
;       if (xmma) {
;         const bf16x8 Ax = *(const bf16x8*)(SA(cur) + lds_byte<KS>(256 + fr, ks * 32 + fq * 8));
; #pragma unroll
;         for (int n = 0; n < NB; ++n) accx[n] = __builtin_amdgcn_mfma_f32_16x16x32_bf16(Bf[n], Ax, accx[n], 0, 0, 0);
;       }
.Lgk_gates_xl:
	s_or_b64 exec, exec, s[20:21]
	s_waitcnt lgkmcnt(1)
	v_mfma_f32_16x16x32_bf16 v[124:127], v[196:199], v[212:215], v[124:127]
	v_mfma_f32_16x16x32_bf16 v[120:123], v[200:203], v[212:215], v[120:123]
	v_mfma_f32_16x16x32_bf16 v[116:119], v[204:207], v[212:215], v[116:119]
	v_mfma_f32_16x16x32_bf16 v[112:115], v[208:211], v[212:215], v[112:115]
	ds_read_b128 v[220:223], v227 offset:7168
	s_waitcnt lgkmcnt(1)
	v_mfma_f32_16x16x32_bf16 v[108:111], v[196:199], v[216:219], v[108:111]
	v_mfma_f32_16x16x32_bf16 v[104:107], v[200:203], v[216:219], v[104:107]
	v_mfma_f32_16x16x32_bf16 v[100:103], v[204:207], v[216:219], v[100:103]
	v_mfma_f32_16x16x32_bf16 v[96:99], v[208:211], v[216:219], v[96:99]
	ds_read_b128 v[212:215], v227 offset:9216
	s_waitcnt lgkmcnt(1)
	v_mfma_f32_16x16x32_bf16 v[92:95], v[196:199], v[220:223], v[92:95]
	v_mfma_f32_16x16x32_bf16 v[88:91], v[200:203], v[220:223], v[88:91]
	v_mfma_f32_16x16x32_bf16 v[84:87], v[204:207], v[220:223], v[84:87]
	v_mfma_f32_16x16x32_bf16 v[80:83], v[208:211], v[220:223], v[80:83]
	ds_read_b128 v[216:219], v227 offset:11264
	s_waitcnt lgkmcnt(1)
	v_mfma_f32_16x16x32_bf16 v[76:79], v[196:199], v[212:215], v[76:79]
	v_mfma_f32_16x16x32_bf16 v[72:75], v[200:203], v[212:215], v[72:75]
	v_mfma_f32_16x16x32_bf16 v[68:71], v[204:207], v[212:215], v[68:71]
	v_mfma_f32_16x16x32_bf16 v[64:67], v[208:211], v[212:215], v[64:67]
	ds_read_b128 v[220:223], v227 offset:13312
	s_waitcnt lgkmcnt(1)
	v_mfma_f32_16x16x32_bf16 v[60:63], v[196:199], v[216:219], v[60:63]
	v_mfma_f32_16x16x32_bf16 v[56:59], v[200:203], v[216:219], v[56:59]
	v_mfma_f32_16x16x32_bf16 v[52:55], v[204:207], v[216:219], v[52:55]
	v_mfma_f32_16x16x32_bf16 v[48:51], v[208:211], v[216:219], v[48:51]
	ds_read_b128 v[212:215], v227 offset:15360
	s_waitcnt lgkmcnt(1)
	v_mfma_f32_16x16x32_bf16 v[44:47], v[196:199], v[220:223], v[44:47]
	v_mfma_f32_16x16x32_bf16 v[40:43], v[200:203], v[220:223], v[40:43]
	v_mfma_f32_16x16x32_bf16 v[36:39], v[204:207], v[220:223], v[36:39]
	v_mfma_f32_16x16x32_bf16 v[32:35], v[208:211], v[220:223], v[32:35]
	s_waitcnt lgkmcnt(0)
	v_mfma_f32_16x16x32_bf16 v[28:31], v[196:199], v[212:215], v[28:31]
	v_mfma_f32_16x16x32_bf16 v[24:27], v[200:203], v[212:215], v[24:27]
	v_mfma_f32_16x16x32_bf16 v[20:23], v[204:207], v[212:215], v[20:23]
	v_mfma_f32_16x16x32_bf16 v[16:19], v[208:211], v[212:215], v[16:19]
	s_and_saveexec_b64 s[20:21], s[0:1]
	s_cbranch_execz .LBB0_1294
	v_add_u32_e32 v228, s22, v182
	ds_read_b128 v[216:219], v228 offset:32768
	ds_read_b128 v[220:223], v228 offset:33792
	s_waitcnt lgkmcnt(1)
	v_mfma_f32_16x16x32_bf16 v[12:15], v[146:149], v[216:219], v[12:15]
	v_mfma_f32_16x16x32_bf16 v[8:11], v[150:153], v[216:219], v[8:11]
	v_mfma_f32_16x16x32_bf16 v[4:7], v[154:157], v[216:219], v[4:7]
	v_mfma_f32_16x16x32_bf16 v[0:3], v[158:161], v[216:219], v[0:3]
	s_waitcnt lgkmcnt(0)
	v_mfma_f32_16x16x32_bf16 v[12:15], v[196:199], v[220:223], v[12:15]
	v_mfma_f32_16x16x32_bf16 v[8:11], v[200:203], v[220:223], v[8:11]
	v_mfma_f32_16x16x32_bf16 v[4:7], v[204:207], v[220:223], v[4:7]
	v_mfma_f32_16x16x32_bf16 v[0:3], v[208:211], v[220:223], v[0:3]
	s_branch .LBB0_1294

; #define WAIT_V0() asm volatile("s_waitcnt vmcnt(0)" ::: "memory")
;     ...
;   GLDS_STAGE(0, 0); WAIT_V0(); __syncthreads();
;   for (int t = 0; t < nt; ++t) {
;     const int cur = t & 1;
;     if (t + 1 < nt) GLDS_STAGE(cur ^ 1, t + 1);
; #pragma unroll
;     for (int ks = 0; ks < KS; ++ks) {
;       bf16x8 At[8], Bf[NB];
; #pragma unroll
;       for (int m = 0; m < 8; ++m) At[m] = *(const bf16x8*)(SA(cur) + lds_byte<KS>(wr * 128 + m * 16 + fr, ks * 32 + fq * 8));
; #pragma unroll
;       for (int n = 0; n < NB; ++n) Bf[n] = *(const bf16x8*)(SB(cur) + lds_byte<KS>(wc * (16 * NB) + n * 16 + fr, ks * 32 + fq * 8));
; #pragma unroll
;       for (int m = 0; m < 8; ++m)
; #pragma unroll
;         for (int n = 0; n < NB; ++n) acc[m][n] = __builtin_amdgcn_mfma_f32_16x16x32_bf16(Bf[n], At[m], acc[m][n], 0, 0, 0);
;       if (xmma) {
;         const bf16x8 Ax = *(const bf16x8*)(SA(cur) + lds_byte<KS>(256 + fr, ks * 32 + fq * 8));
; #pragma unroll
;         for (int n = 0; n < NB; ++n) accx[n] = __builtin_amdgcn_mfma_f32_16x16x32_bf16(Bf[n], Ax, accx[n], 0, 0, 0);
;       }
.LBB0_1350:
	s_and_b32 s7, s3, 1
	s_xor_b32 s22, s7, 1
	s_mul_i32 s22, s22, 0x10800
	s_mul_i32 s7, s7, 0x10800
	v_or_b32_e32 v128, s7, v191
	v_add_u32_e32 v234, v128, v203
	v_add_u32_e32 v240, v128, v202
	v_readfirstlane_b32 s100, v192
	ds_read_b128 v[146:149], v234 offset:34816
	ds_read_b128 v[220:223], v240
	ds_read_b128 v[150:153], v234 offset:36864
	ds_read_b128 v[154:157], v234 offset:38912
	ds_read_b128 v[158:161], v234 offset:40960
	ds_read_b128 v[224:227], v240 offset:2048
	s_add_i32 s100, s100, s22
	s_waitcnt lgkmcnt(1)
	v_mfma_f32_16x16x32_bf16 v[142:145], v[146:149], v[220:223], v[142:145]
	v_mfma_f32_16x16x32_bf16 v[138:141], v[150:153], v[220:223], v[138:141]
	v_mfma_f32_16x16x32_bf16 v[134:137], v[154:157], v[220:223], v[134:137]
	v_mfma_f32_16x16x32_bf16 v[130:133], v[158:161], v[220:223], v[130:133]
	ds_read_b128 v[228:231], v240 offset:4096
	s_mov_b32 m0, s100
	v_lshl_add_u64 v[238:239], v[162:163], 0, s[70:71]
	global_load_lds_dwordx4 v[238:239], off
	s_waitcnt lgkmcnt(1)
	v_mfma_f32_16x16x32_bf16 v[124:127], v[146:149], v[224:227], v[124:127]
	v_mfma_f32_16x16x32_bf16 v[120:123], v[150:153], v[224:227], v[120:123]
	v_mfma_f32_16x16x32_bf16 v[116:119], v[154:157], v[224:227], v[116:119]
	v_mfma_f32_16x16x32_bf16 v[112:115], v[158:161], v[224:227], v[112:115]
	ds_read_b128 v[220:223], v240 offset:6144
	s_add_i32 m0, s100, 0x8800
	v_lshl_add_u64 v[238:239], v[170:171], 0, s[70:71]
	global_load_lds_dwordx4 v[238:239], off
	s_waitcnt lgkmcnt(1)
	v_mfma_f32_16x16x32_bf16 v[108:111], v[146:149], v[228:231], v[108:111]
	v_mfma_f32_16x16x32_bf16 v[104:107], v[150:153], v[228:231], v[104:107]
	v_mfma_f32_16x16x32_bf16 v[100:103], v[154:157], v[228:231], v[100:103]
	v_mfma_f32_16x16x32_bf16 v[96:99], v[158:161], v[228:231], v[96:99]
	ds_read_b128 v[224:227], v240 offset:8192
	s_add_i32 m0, s100, 0x2000
	v_lshl_add_u64 v[238:239], v[164:165], 0, s[70:71]
	global_load_lds_dwordx4 v[238:239], off
	s_waitcnt lgkmcnt(1)
	v_mfma_f32_16x16x32_bf16 v[92:95], v[146:149], v[220:223], v[92:95]
	v_mfma_f32_16x16x32_bf16 v[88:91], v[150:153], v[220:223], v[88:91]
	v_mfma_f32_16x16x32_bf16 v[84:87], v[154:157], v[220:223], v[84:87]
	v_mfma_f32_16x16x32_bf16 v[80:83], v[158:161], v[220:223], v[80:83]
	ds_read_b128 v[228:231], v240 offset:10240
	s_add_i32 m0, s100, 0xa800
	v_lshl_add_u64 v[238:239], v[172:173], 0, s[70:71]
	global_load_lds_dwordx4 v[238:239], off
	s_waitcnt lgkmcnt(1)
	v_mfma_f32_16x16x32_bf16 v[76:79], v[146:149], v[224:227], v[76:79]
	v_mfma_f32_16x16x32_bf16 v[72:75], v[150:153], v[224:227], v[72:75]
	v_mfma_f32_16x16x32_bf16 v[68:71], v[154:157], v[224:227], v[68:71]
	v_mfma_f32_16x16x32_bf16 v[64:67], v[158:161], v[224:227], v[64:67]
	ds_read_b128 v[204:207], v234 offset:35840
	ds_read_b128 v[220:223], v240 offset:12288
	s_add_i32 m0, s100, 0x4000
	v_lshl_add_u64 v[238:239], v[166:167], 0, s[70:71]
	global_load_lds_dwordx4 v[238:239], off
	s_waitcnt lgkmcnt(2)
	v_mfma_f32_16x16x32_bf16 v[60:63], v[146:149], v[228:231], v[60:63]
	v_mfma_f32_16x16x32_bf16 v[56:59], v[150:153], v[228:231], v[56:59]
	v_mfma_f32_16x16x32_bf16 v[52:55], v[154:157], v[228:231], v[52:55]
	v_mfma_f32_16x16x32_bf16 v[48:51], v[158:161], v[228:231], v[48:51]
	ds_read_b128 v[208:211], v234 offset:37888
	ds_read_b128 v[224:227], v240 offset:14336
	s_add_i32 m0, s100, 0xc800
	v_lshl_add_u64 v[238:239], v[174:175], 0, s[70:71]
	global_load_lds_dwordx4 v[238:239], off
	s_waitcnt lgkmcnt(2)
	v_mfma_f32_16x16x32_bf16 v[44:47], v[146:149], v[220:223], v[44:47]
	v_mfma_f32_16x16x32_bf16 v[40:43], v[150:153], v[220:223], v[40:43]
	v_mfma_f32_16x16x32_bf16 v[36:39], v[154:157], v[220:223], v[36:39]
	v_mfma_f32_16x16x32_bf16 v[32:35], v[158:161], v[220:223], v[32:35]
	ds_read_b128 v[212:215], v234 offset:39936
	ds_read_b128 v[228:231], v240 offset:1024
	s_add_i32 m0, s100, 0x6000
	v_lshl_add_u64 v[238:239], v[168:169], 0, s[70:71]
	global_load_lds_dwordx4 v[238:239], off
	s_waitcnt lgkmcnt(2)
	v_mfma_f32_16x16x32_bf16 v[28:31], v[146:149], v[224:227], v[28:31]
	v_mfma_f32_16x16x32_bf16 v[24:27], v[150:153], v[224:227], v[24:27]
	v_mfma_f32_16x16x32_bf16 v[20:23], v[154:157], v[224:227], v[20:23]
	v_mfma_f32_16x16x32_bf16 v[16:19], v[158:161], v[224:227], v[16:19]
	ds_read_b128 v[216:219], v234 offset:41984
	ds_read_b128 v[220:223], v240 offset:3072
	s_add_i32 m0, s100, 0xe800
	v_lshl_add_u64 v[238:239], v[176:177], 0, s[70:71]
	global_load_lds_dwordx4 v[238:239], off
	s_waitcnt lgkmcnt(1)
	v_mfma_f32_16x16x32_bf16 v[142:145], v[204:207], v[228:231], v[142:145]
	v_mfma_f32_16x16x32_bf16 v[138:141], v[208:211], v[228:231], v[138:141]
	v_mfma_f32_16x16x32_bf16 v[134:137], v[212:215], v[228:231], v[134:137]
	v_mfma_f32_16x16x32_bf16 v[130:133], v[216:219], v[228:231], v[130:133]
	ds_read_b128 v[224:227], v240 offset:5120
	s_and_saveexec_b64 s[20:21], s[68:69]
	s_cbranch_execz .Lgk_out_xl
	v_readfirstlane_b32 s101, v201
	s_add_i32 s101, s101, s22
	s_add_i32 m0, s101, 0x8000
	v_lshl_add_u64 v[238:239], v[178:179], 0, s[70:71]
	global_load_lds_dwordx4 v[238:239], off
;     ...
;     for (int ks = 0; ks < KS; ++ks) {
;       bf16x8 At[8], Bf[NB];
; #pragma unroll
;       for (int m = 0; m < 8; ++m) At[m] = *(const bf16x8*)(SA(cur) + lds_byte<KS>(wr * 128 + m * 16 + fr, ks * 32 + fq * 8));
; #pragma unroll
;       for (int n = 0; n < NB; ++n) Bf[n] = *(const bf16x8*)(SB(cur) + lds_byte<KS>(wc * (16 * NB) + n * 16 + fr, ks * 32 + fq * 8));
; #pragma unroll
;       for (int m = 0; m < 8; ++m)
; #pragma unroll
;         for (int n = 0; n < NB; ++n) acc[m][n] = __builtin_amdgcn_mfma_f32_16x16x32_bf16(Bf[n], At[m], acc[m][n], 0, 0, 0);
;       if (xmma) {
;         const bf16x8 Ax = *(const bf16x8*)(SA(cur) + lds_byte<KS>(256 + fr, ks * 32 + fq * 8));
; #pragma unroll
;         for (int n = 0; n < NB; ++n) accx[n] = __builtin_amdgcn_mfma_f32_16x16x32_bf16(Bf[n], Ax, accx[n], 0, 0, 0);
;       }
.Lgk_out_xl:
	s_or_b64 exec, exec, s[20:21]
	s_waitcnt lgkmcnt(1)
	v_mfma_f32_16x16x32_bf16 v[124:127], v[204:207], v[220:223], v[124:127]
	v_mfma_f32_16x16x32_bf16 v[120:123], v[208:211], v[220:223], v[120:123]
	v_mfma_f32_16x16x32_bf16 v[116:119], v[212:215], v[220:223], v[116:119]
	v_mfma_f32_16x16x32_bf16 v[112:115], v[216:219], v[220:223], v[112:115]
	ds_read_b128 v[228:231], v240 offset:7168
	s_waitcnt lgkmcnt(1)
	v_mfma_f32_16x16x32_bf16 v[108:111], v[204:207], v[224:227], v[108:111]
	v_mfma_f32_16x16x32_bf16 v[104:107], v[208:211], v[224:227], v[104:107]
	v_mfma_f32_16x16x32_bf16 v[100:103], v[212:215], v[224:227], v[100:103]
	v_mfma_f32_16x16x32_bf16 v[96:99], v[216:219], v[224:227], v[96:99]
	ds_read_b128 v[220:223], v240 offset:9216
	s_waitcnt lgkmcnt(1)
	v_mfma_f32_16x16x32_bf16 v[92:95], v[204:207], v[228:231], v[92:95]
	v_mfma_f32_16x16x32_bf16 v[88:91], v[208:211], v[228:231], v[88:91]
	v_mfma_f32_16x16x32_bf16 v[84:87], v[212:215], v[228:231], v[84:87]
	v_mfma_f32_16x16x32_bf16 v[80:83], v[216:219], v[228:231], v[80:83]
	ds_read_b128 v[224:227], v240 offset:11264
	s_waitcnt lgkmcnt(1)
	v_mfma_f32_16x16x32_bf16 v[76:79], v[204:207], v[220:223], v[76:79]
	v_mfma_f32_16x16x32_bf16 v[72:75], v[208:211], v[220:223], v[72:75]
	v_mfma_f32_16x16x32_bf16 v[68:71], v[212:215], v[220:223], v[68:71]
	v_mfma_f32_16x16x32_bf16 v[64:67], v[216:219], v[220:223], v[64:67]
	ds_read_b128 v[228:231], v240 offset:13312
	s_waitcnt lgkmcnt(1)
	v_mfma_f32_16x16x32_bf16 v[60:63], v[204:207], v[224:227], v[60:63]
	v_mfma_f32_16x16x32_bf16 v[56:59], v[208:211], v[224:227], v[56:59]
	v_mfma_f32_16x16x32_bf16 v[52:55], v[212:215], v[224:227], v[52:55]
	v_mfma_f32_16x16x32_bf16 v[48:51], v[216:219], v[224:227], v[48:51]
	ds_read_b128 v[220:223], v240 offset:15360
	s_waitcnt lgkmcnt(1)
	v_mfma_f32_16x16x32_bf16 v[44:47], v[204:207], v[228:231], v[44:47]
	v_mfma_f32_16x16x32_bf16 v[40:43], v[208:211], v[228:231], v[40:43]
	v_mfma_f32_16x16x32_bf16 v[36:39], v[212:215], v[228:231], v[36:39]
	v_mfma_f32_16x16x32_bf16 v[32:35], v[216:219], v[228:231], v[32:35]
	s_waitcnt lgkmcnt(0)
	v_mfma_f32_16x16x32_bf16 v[28:31], v[204:207], v[220:223], v[28:31]
	v_mfma_f32_16x16x32_bf16 v[24:27], v[208:211], v[220:223], v[24:27]
	v_mfma_f32_16x16x32_bf16 v[20:23], v[212:215], v[220:223], v[20:23]
	v_mfma_f32_16x16x32_bf16 v[16:19], v[216:219], v[220:223], v[16:19]
	s_and_saveexec_b64 s[20:21], s[4:5]
	s_cbranch_execz .LBB0_1349
	v_add_u32_e32 v241, s7, v191
	ds_read_b128 v[224:227], v241 offset:32768
	ds_read_b128 v[228:231], v241 offset:33792
	s_waitcnt lgkmcnt(1)
	v_mfma_f32_16x16x32_bf16 v[12:15], v[146:149], v[224:227], v[12:15]
	v_mfma_f32_16x16x32_bf16 v[8:11], v[150:153], v[224:227], v[8:11]
	v_mfma_f32_16x16x32_bf16 v[4:7], v[154:157], v[224:227], v[4:7]
	v_mfma_f32_16x16x32_bf16 v[0:3], v[158:161], v[224:227], v[0:3]
	s_waitcnt lgkmcnt(0)
	v_mfma_f32_16x16x32_bf16 v[12:15], v[204:207], v[228:231], v[12:15]
	v_mfma_f32_16x16x32_bf16 v[8:11], v[208:211], v[228:231], v[8:11]
	v_mfma_f32_16x16x32_bf16 v[4:7], v[212:215], v[228:231], v[4:7]
	v_mfma_f32_16x16x32_bf16 v[0:3], v[216:219], v[228:231], v[0:3]
	s_branch .LBB0_1349

; #define WAIT_V0() asm volatile("s_waitcnt vmcnt(0)" ::: "memory")
;     ...
;   GLDS_STAGE(0, 0); WAIT_V0(); __syncthreads();
;   for (int t = 0; t < nt; ++t) {
;     const int cur = t & 1;
;     if (t + 1 < nt) GLDS_STAGE(cur ^ 1, t + 1);
; #pragma unroll
;     for (int ks = 0; ks < KS; ++ks) {
;       bf16x8 At[8], Bf[NB];
; #pragma unroll
;       for (int m = 0; m < 8; ++m) At[m] = *(const bf16x8*)(SA(cur) + lds_byte<KS>(wr * 128 + m * 16 + fr, ks * 32 + fq * 8));
; #pragma unroll
;       for (int n = 0; n < NB; ++n) Bf[n] = *(const bf16x8*)(SB(cur) + lds_byte<KS>(wc * (16 * NB) + n * 16 + fr, ks * 32 + fq * 8));
; #pragma unroll
;       for (int m = 0; m < 8; ++m)
; #pragma unroll
;         for (int n = 0; n < NB; ++n) acc[m][n] = __builtin_amdgcn_mfma_f32_16x16x32_bf16(Bf[n], At[m], acc[m][n], 0, 0, 0);
;       if (xmma) {
;         const bf16x8 Ax = *(const bf16x8*)(SA(cur) + lds_byte<KS>(256 + fr, ks * 32 + fq * 8));
; #pragma unroll
;         for (int n = 0; n < NB; ++n) accx[n] = __builtin_amdgcn_mfma_f32_16x16x32_bf16(Bf[n], Ax, accx[n], 0, 0, 0);
;       }
.LBB0_1744:
	s_and_b32 s5, s3, 1
	s_xor_b32 s17, s5, 1
	s_mul_i32 s17, s17, 0x10800
	s_mul_i32 s5, s5, 0x10800
	v_or_b32_e32 v128, s5, v191
	v_add_u32_e32 v234, v128, v203
	v_add_u32_e32 v240, v128, v202
	v_readfirstlane_b32 s100, v192
	ds_read_b128 v[146:149], v234 offset:34816
	ds_read_b128 v[220:223], v240
	ds_read_b128 v[150:153], v234 offset:36864
	ds_read_b128 v[154:157], v234 offset:38912
	ds_read_b128 v[158:161], v234 offset:40960
	ds_read_b128 v[224:227], v240 offset:2048
	s_add_i32 s100, s100, s17
	s_waitcnt lgkmcnt(1)
	v_mfma_f32_16x16x32_bf16 v[142:145], v[146:149], v[220:223], v[142:145]
	v_mfma_f32_16x16x32_bf16 v[138:141], v[150:153], v[220:223], v[138:141]
	v_mfma_f32_16x16x32_bf16 v[134:137], v[154:157], v[220:223], v[134:137]
	v_mfma_f32_16x16x32_bf16 v[130:133], v[158:161], v[220:223], v[130:133]
	ds_read_b128 v[228:231], v240 offset:4096
	s_mov_b32 m0, s100
	v_lshl_add_u64 v[238:239], v[162:163], 0, s[66:67]
	global_load_lds_dwordx4 v[238:239], off
	s_waitcnt lgkmcnt(1)
	v_mfma_f32_16x16x32_bf16 v[124:127], v[146:149], v[224:227], v[124:127]
	v_mfma_f32_16x16x32_bf16 v[120:123], v[150:153], v[224:227], v[120:123]
	v_mfma_f32_16x16x32_bf16 v[116:119], v[154:157], v[224:227], v[116:119]
	v_mfma_f32_16x16x32_bf16 v[112:115], v[158:161], v[224:227], v[112:115]
	ds_read_b128 v[220:223], v240 offset:6144
	s_add_i32 m0, s100, 0x8800
	v_lshl_add_u64 v[238:239], v[170:171], 0, s[66:67]
	global_load_lds_dwordx4 v[238:239], off
	s_waitcnt lgkmcnt(1)
	v_mfma_f32_16x16x32_bf16 v[108:111], v[146:149], v[228:231], v[108:111]
	v_mfma_f32_16x16x32_bf16 v[104:107], v[150:153], v[228:231], v[104:107]
	v_mfma_f32_16x16x32_bf16 v[100:103], v[154:157], v[228:231], v[100:103]
	v_mfma_f32_16x16x32_bf16 v[96:99], v[158:161], v[228:231], v[96:99]
	ds_read_b128 v[224:227], v240 offset:8192
	s_add_i32 m0, s100, 0x2000
	v_lshl_add_u64 v[238:239], v[164:165], 0, s[66:67]
	global_load_lds_dwordx4 v[238:239], off
	s_waitcnt lgkmcnt(1)
	v_mfma_f32_16x16x32_bf16 v[92:95], v[146:149], v[220:223], v[92:95]
	v_mfma_f32_16x16x32_bf16 v[88:91], v[150:153], v[220:223], v[88:91]
	v_mfma_f32_16x16x32_bf16 v[84:87], v[154:157], v[220:223], v[84:87]
	v_mfma_f32_16x16x32_bf16 v[80:83], v[158:161], v[220:223], v[80:83]
	ds_read_b128 v[228:231], v240 offset:10240
	s_add_i32 m0, s100, 0xa800
	v_lshl_add_u64 v[238:239], v[172:173], 0, s[66:67]
	global_load_lds_dwordx4 v[238:239], off
	s_waitcnt lgkmcnt(1)
	v_mfma_f32_16x16x32_bf16 v[76:79], v[146:149], v[224:227], v[76:79]
	v_mfma_f32_16x16x32_bf16 v[72:75], v[150:153], v[224:227], v[72:75]
	v_mfma_f32_16x16x32_bf16 v[68:71], v[154:157], v[224:227], v[68:71]
	v_mfma_f32_16x16x32_bf16 v[64:67], v[158:161], v[224:227], v[64:67]
	ds_read_b128 v[204:207], v234 offset:35840
	ds_read_b128 v[220:223], v240 offset:12288
	s_add_i32 m0, s100, 0x4000
	v_lshl_add_u64 v[238:239], v[166:167], 0, s[66:67]
	global_load_lds_dwordx4 v[238:239], off
	s_waitcnt lgkmcnt(2)
	v_mfma_f32_16x16x32_bf16 v[60:63], v[146:149], v[228:231], v[60:63]
	v_mfma_f32_16x16x32_bf16 v[56:59], v[150:153], v[228:231], v[56:59]
	v_mfma_f32_16x16x32_bf16 v[52:55], v[154:157], v[228:231], v[52:55]
	v_mfma_f32_16x16x32_bf16 v[48:51], v[158:161], v[228:231], v[48:51]
	ds_read_b128 v[208:211], v234 offset:37888
	ds_read_b128 v[224:227], v240 offset:14336
	s_add_i32 m0, s100, 0xc800
	v_lshl_add_u64 v[238:239], v[174:175], 0, s[66:67]
	global_load_lds_dwordx4 v[238:239], off
	s_waitcnt lgkmcnt(2)
	v_mfma_f32_16x16x32_bf16 v[44:47], v[146:149], v[220:223], v[44:47]
	v_mfma_f32_16x16x32_bf16 v[40:43], v[150:153], v[220:223], v[40:43]
	v_mfma_f32_16x16x32_bf16 v[36:39], v[154:157], v[220:223], v[36:39]
	v_mfma_f32_16x16x32_bf16 v[32:35], v[158:161], v[220:223], v[32:35]
	ds_read_b128 v[212:215], v234 offset:39936
	ds_read_b128 v[228:231], v240 offset:1024
	s_add_i32 m0, s100, 0x6000
	v_lshl_add_u64 v[238:239], v[168:169], 0, s[66:67]
	global_load_lds_dwordx4 v[238:239], off
	s_waitcnt lgkmcnt(2)
	v_mfma_f32_16x16x32_bf16 v[28:31], v[146:149], v[224:227], v[28:31]
	v_mfma_f32_16x16x32_bf16 v[24:27], v[150:153], v[224:227], v[24:27]
	v_mfma_f32_16x16x32_bf16 v[20:23], v[154:157], v[224:227], v[20:23]
	v_mfma_f32_16x16x32_bf16 v[16:19], v[158:161], v[224:227], v[16:19]
	ds_read_b128 v[216:219], v234 offset:41984
	ds_read_b128 v[220:223], v240 offset:3072
	s_add_i32 m0, s100, 0xe800
	v_lshl_add_u64 v[238:239], v[176:177], 0, s[66:67]
	global_load_lds_dwordx4 v[238:239], off
	s_waitcnt lgkmcnt(1)
	v_mfma_f32_16x16x32_bf16 v[142:145], v[204:207], v[228:231], v[142:145]
	v_mfma_f32_16x16x32_bf16 v[138:141], v[208:211], v[228:231], v[138:141]
	v_mfma_f32_16x16x32_bf16 v[134:137], v[212:215], v[228:231], v[134:137]
	v_mfma_f32_16x16x32_bf16 v[130:133], v[216:219], v[228:231], v[130:133]
	ds_read_b128 v[224:227], v240 offset:5120
	s_and_saveexec_b64 s[20:21], s[64:65]
	s_cbranch_execz .Lgk_down_xl
	v_readfirstlane_b32 s101, v201
	s_add_i32 s101, s101, s17
	s_add_i32 m0, s101, 0x8000
	v_lshl_add_u64 v[238:239], v[178:179], 0, s[66:67]
	global_load_lds_dwordx4 v[238:239], off
;     ...
;     for (int ks = 0; ks < KS; ++ks) {
;       bf16x8 At[8], Bf[NB];
; #pragma unroll
;       for (int m = 0; m < 8; ++m) At[m] = *(const bf16x8*)(SA(cur) + lds_byte<KS>(wr * 128 + m * 16 + fr, ks * 32 + fq * 8));
; #pragma unroll
;       for (int n = 0; n < NB; ++n) Bf[n] = *(const bf16x8*)(SB(cur) + lds_byte<KS>(wc * (16 * NB) + n * 16 + fr, ks * 32 + fq * 8));
; #pragma unroll
;       for (int m = 0; m < 8; ++m)
; #pragma unroll
;         for (int n = 0; n < NB; ++n) acc[m][n] = __builtin_amdgcn_mfma_f32_16x16x32_bf16(Bf[n], At[m], acc[m][n], 0, 0, 0);
;       if (xmma) {
;         const bf16x8 Ax = *(const bf16x8*)(SA(cur) + lds_byte<KS>(256 + fr, ks * 32 + fq * 8));
; #pragma unroll
;         for (int n = 0; n < NB; ++n) accx[n] = __builtin_amdgcn_mfma_f32_16x16x32_bf16(Bf[n], Ax, accx[n], 0, 0, 0);
;       }
.Lgk_down_xl:
	s_or_b64 exec, exec, s[20:21]
	s_waitcnt lgkmcnt(1)
	v_mfma_f32_16x16x32_bf16 v[124:127], v[204:207], v[220:223], v[124:127]
	v_mfma_f32_16x16x32_bf16 v[120:123], v[208:211], v[220:223], v[120:123]
	v_mfma_f32_16x16x32_bf16 v[116:119], v[212:215], v[220:223], v[116:119]
	v_mfma_f32_16x16x32_bf16 v[112:115], v[216:219], v[220:223], v[112:115]
	ds_read_b128 v[228:231], v240 offset:7168
	s_waitcnt lgkmcnt(1)
	v_mfma_f32_16x16x32_bf16 v[108:111], v[204:207], v[224:227], v[108:111]
	v_mfma_f32_16x16x32_bf16 v[104:107], v[208:211], v[224:227], v[104:107]
	v_mfma_f32_16x16x32_bf16 v[100:103], v[212:215], v[224:227], v[100:103]
	v_mfma_f32_16x16x32_bf16 v[96:99], v[216:219], v[224:227], v[96:99]
	ds_read_b128 v[220:223], v240 offset:9216
	s_waitcnt lgkmcnt(1)
	v_mfma_f32_16x16x32_bf16 v[92:95], v[204:207], v[228:231], v[92:95]
	v_mfma_f32_16x16x32_bf16 v[88:91], v[208:211], v[228:231], v[88:91]
	v_mfma_f32_16x16x32_bf16 v[84:87], v[212:215], v[228:231], v[84:87]
	v_mfma_f32_16x16x32_bf16 v[80:83], v[216:219], v[228:231], v[80:83]
	ds_read_b128 v[224:227], v240 offset:11264
	s_waitcnt lgkmcnt(1)
	v_mfma_f32_16x16x32_bf16 v[76:79], v[204:207], v[220:223], v[76:79]
	v_mfma_f32_16x16x32_bf16 v[72:75], v[208:211], v[220:223], v[72:75]
	v_mfma_f32_16x16x32_bf16 v[68:71], v[212:215], v[220:223], v[68:71]
	v_mfma_f32_16x16x32_bf16 v[64:67], v[216:219], v[220:223], v[64:67]
	ds_read_b128 v[228:231], v240 offset:13312
	s_waitcnt lgkmcnt(1)
	v_mfma_f32_16x16x32_bf16 v[60:63], v[204:207], v[224:227], v[60:63]
	v_mfma_f32_16x16x32_bf16 v[56:59], v[208:211], v[224:227], v[56:59]
	v_mfma_f32_16x16x32_bf16 v[52:55], v[212:215], v[224:227], v[52:55]
	v_mfma_f32_16x16x32_bf16 v[48:51], v[216:219], v[224:227], v[48:51]
	ds_read_b128 v[220:223], v240 offset:15360
	s_waitcnt lgkmcnt(1)
	v_mfma_f32_16x16x32_bf16 v[44:47], v[204:207], v[228:231], v[44:47]
	v_mfma_f32_16x16x32_bf16 v[40:43], v[208:211], v[228:231], v[40:43]
	v_mfma_f32_16x16x32_bf16 v[36:39], v[212:215], v[228:231], v[36:39]
	v_mfma_f32_16x16x32_bf16 v[32:35], v[216:219], v[228:231], v[32:35]
	s_waitcnt lgkmcnt(0)
	v_mfma_f32_16x16x32_bf16 v[28:31], v[204:207], v[220:223], v[28:31]
	v_mfma_f32_16x16x32_bf16 v[24:27], v[208:211], v[220:223], v[24:27]
	v_mfma_f32_16x16x32_bf16 v[20:23], v[212:215], v[220:223], v[20:23]
	v_mfma_f32_16x16x32_bf16 v[16:19], v[216:219], v[220:223], v[16:19]
	s_and_saveexec_b64 s[20:21], s[62:63]
	s_cbranch_execz .LBB0_1743
	v_add_u32_e32 v241, s5, v191
	ds_read_b128 v[224:227], v241 offset:32768
	ds_read_b128 v[228:231], v241 offset:33792
	s_waitcnt lgkmcnt(1)
	v_mfma_f32_16x16x32_bf16 v[12:15], v[146:149], v[224:227], v[12:15]
	v_mfma_f32_16x16x32_bf16 v[8:11], v[150:153], v[224:227], v[8:11]
	v_mfma_f32_16x16x32_bf16 v[4:7], v[154:157], v[224:227], v[4:7]
	v_mfma_f32_16x16x32_bf16 v[0:3], v[158:161], v[224:227], v[0:3]
	s_waitcnt lgkmcnt(0)
	v_mfma_f32_16x16x32_bf16 v[12:15], v[204:207], v[228:231], v[12:15]
	v_mfma_f32_16x16x32_bf16 v[8:11], v[208:211], v[228:231], v[8:11]
	v_mfma_f32_16x16x32_bf16 v[4:7], v[212:215], v[228:231], v[4:7]
	v_mfma_f32_16x16x32_bf16 v[0:3], v[216:219], v[228:231], v[0:3]
	s_branch .LBB0_1743

; __global__ void __launch_bounds__(512) mega(Params p) {
	.amdhsa_kernel _Z4mega6Params
		.amdhsa_group_segment_fixed_size 157712
		.amdhsa_private_segment_fixed_size 0
		.amdhsa_kernarg_size 480
		.amdhsa_user_sgpr_count 2
		.amdhsa_user_sgpr_dispatch_ptr 0
		.amdhsa_user_sgpr_queue_ptr 0
		.amdhsa_user_sgpr_kernarg_segment_ptr 1
		.amdhsa_user_sgpr_dispatch_id 0
		.amdhsa_user_sgpr_kernarg_preload_length 0
		.amdhsa_user_sgpr_kernarg_preload_offset 0
		.amdhsa_user_sgpr_private_segment_size 0
		.amdhsa_uses_dynamic_stack 0
		.amdhsa_enable_private_segment 0
		.amdhsa_system_sgpr_workgroup_id_x 1
		.amdhsa_system_sgpr_workgroup_id_y 0
		.amdhsa_system_sgpr_workgroup_id_z 0
		.amdhsa_system_sgpr_workgroup_info 0
		.amdhsa_system_vgpr_workitem_id 2
		.amdhsa_next_free_vgpr 256
		.amdhsa_next_free_sgpr 102
		.amdhsa_accum_offset 256
		.amdhsa_reserve_vcc 1
		.amdhsa_float_round_mode_32 0
		.amdhsa_float_round_mode_16_64 0
		.amdhsa_float_denorm_mode_32 3
		.amdhsa_float_denorm_mode_16_64 3
		.amdhsa_dx10_clamp 1
		.amdhsa_ieee_mode 1
		.amdhsa_fp16_overflow 0
		.amdhsa_tg_split 0
		.amdhsa_exception_fp_ieee_invalid_op 0
		.amdhsa_exception_fp_denorm_src 0
		.amdhsa_exception_fp_ieee_div_zero 0
		.amdhsa_exception_fp_ieee_overflow 0
		.amdhsa_exception_fp_ieee_underflow 0
		.amdhsa_exception_fp_ieee_inexact 0
		.amdhsa_exception_int_div_zero 0
	.end_amdhsa_kernel

; __global__ void __launch_bounds__(512) mega(Params p) {
amdhsa.kernels:
  - .agpr_count:     0
    .args:
      - .offset:         0
        .size:           224
        .value_kind:     by_value
      - .offset:         224
        .size:           4
        .value_kind:     hidden_block_count_x
      - .offset:         228
        .size:           4
        .value_kind:     hidden_block_count_y
      - .offset:         232
        .size:           4
        .value_kind:     hidden_block_count_z
      - .offset:         236
        .size:           2
        .value_kind:     hidden_group_size_x
      - .offset:         238
        .size:           2
        .value_kind:     hidden_group_size_y
      - .offset:         240
        .size:           2
        .value_kind:     hidden_group_size_z
      - .offset:         242
        .size:           2
        .value_kind:     hidden_remainder_x
      - .offset:         244
        .size:           2
        .value_kind:     hidden_remainder_y
      - .offset:         246
        .size:           2
        .value_kind:     hidden_remainder_z
      - .offset:         264
        .size:           8
        .value_kind:     hidden_global_offset_x
      - .offset:         272
        .size:           8
        .value_kind:     hidden_global_offset_y
      - .offset:         280
        .size:           8
        .value_kind:     hidden_global_offset_z
      - .offset:         288
        .size:           2
        .value_kind:     hidden_grid_dims
      - .offset:         312
        .size:           8
        .value_kind:     hidden_multigrid_sync_arg
    .group_segment_fixed_size: 157712
    .kernarg_segment_align: 8
    .kernarg_segment_size: 480
    .language:       OpenCL C
    .language_version:
      - 2
      - 0
    .max_flat_workgroup_size: 512
    .name:           _Z4mega6Params
    .private_segment_fixed_size: 0
    .sgpr_count:     108
    .sgpr_spill_count: 79
    .symbol:         _Z4mega6Params.kd
    .uniform_work_group_size: 1
    .uses_dynamic_stack: false
    .vgpr_count:     256
    .vgpr_spill_count: 0
    .wavefront_size: 64
